# P0 end: cooperative-groups grid sync replaced by the kernel's own XCD-hierarchical barrier (shared code, return selector)
# baseline (speedup 1.0000x reference)
; #define LAS __attribute__((address_space(3)))
; __global__ void __launch_bounds__(NTHR, 2) mega(Params p) {
;     extern __shared__ __attribute__((aligned(16))) unsigned char lds[];
;     cg::grid_group grid = cg::this_grid();
;     const int G = gridDim.x, bid = blockIdx.x;
;     const int wv = __builtin_amdgcn_readfirstlane(threadIdx.x >> 6);
;     volatile LAS unsigned* xst = (volatile LAS unsigned*)((LAS unsigned char*)lds + (LDS_BYTES - 16));
;     if (threadIdx.x == 0) { xst[0] = 0u; xst[1] = 0u; }
;     __syncthreads();
;     const XcdBarrier xbar = xcd_barrier_post((unsigned*)(p.ws + WS_BAR), xst);
_Z4mega6Params:
	s_mov_b32 s99, 0
	s_load_dwordx16 s[16:31], s[0:1], 0x80
	s_load_dword s62, s[0:1], 0xc8
	s_load_dwordx2 s[34:35], s[0:1], 0xc0
	s_add_u32 s6, s0, 0xc0
	v_and_b32_e32 v1, 0x3ff, v0
	s_addc_u32 s7, s1, 0
	v_readfirstlane_b32 s3, v1
	v_cmp_eq_u32_e32 vcc, 0, v1
	s_and_saveexec_b64 s[4:5], vcc
	s_cbranch_execz .LBB0_2
	s_add_i32 s8, 0, 0x23ff0
	v_mov_b32_e32 v2, 0
	v_mov_b32_e32 v3, s8
	s_add_i32 s8, 0, 0x23ff4
	ds_write_b32 v3, v2
	v_mov_b32_e32 v3, s8
	ds_write_b32 v3, v2

; __device__ __forceinline__ int otid(int wv) { int t; asm volatile("v_mbcnt_lo_u32_b32 %0, -1, 0\n\tv_mbcnt_hi_u32_b32 %0, -1, %0\n\tv_lshl_add_u32 %0, %1, 6, %0" : "=&v"(t) : "s"(wv)); return t; }
; __global__ void __launch_bounds__(NTHR, 2) mega(Params p) {
;     ...
;     grid.sync();
;     }
;     {
;     WSPTRS
;     const int tid = otid(wv);
;     if (bid < 26 + 88) {
;         const float* W; int ld, perm = 0, nb, grp; const float* sh; float* bo;
;         if (bid < 8) { W = p.a_w_in; ld = 2048; sh = mod; bo = biasG1; nb = 2048; grp = bid; }
;         else if (bid < 14) { W = p.b_w_qkv; ld = 1536; sh = mod + 3 * MODW; bo = biasG1 + 3 * 2048; nb = 1536; grp = bid - 8; }
;         else if (bid < 18) { W = p.c_w_in; ld = 1024; sh = mod + 6 * MODW; bo = biasG1 + 6 * 2048; nb = 1024; grp = bid - 14; }
;         else if (bid < 26) { W = p.a_w_in + (size_t)1024 * 2048; ld = 2048; sh = mod + 9 * MODW; bo = biasG1 + 9 * 2048; nb = 2048; grp = bid - 18; }
;         else { const int li = (bid - 26) / 22; W = p.f_w_up + (size_t)li * 1024 * NUP; ld = NUP; perm = 1; sh = mod + (size_t)li * 3 * MODW + 3 * DM; bo = biasUP + (size_t)li * 3 * NUP; nb = NUP; grp = (bid - 26) % 22; }
;         bias_task(wv, W, ld, perm, sh, bo, nb, grp, ldsf);
.LBB0_60:
	v_writelane_b32 v252, s0, 0
	v_writelane_b32 v252, s1, 1
	v_writelane_b32 v252, s3, 2
	v_writelane_b32 v252, s4, 3
	v_writelane_b32 v252, s5, 4
	v_writelane_b32 v252, s6, 5
	v_writelane_b32 v252, s7, 6
	v_writelane_b32 v252, s8, 7
	v_writelane_b32 v252, s9, 8
	v_writelane_b32 v252, s10, 9
	v_writelane_b32 v252, s11, 10
	v_writelane_b32 v252, s12, 11
	v_writelane_b32 v252, s13, 12
	v_writelane_b32 v252, s14, 13
	v_writelane_b32 v252, s15, 14
	v_writelane_b32 v252, s16, 15
	v_writelane_b32 v252, s17, 16
	v_writelane_b32 v252, s20, 17
	v_writelane_b32 v252, s21, 18
	v_writelane_b32 v252, s22, 19
	v_writelane_b32 v252, s23, 20
	v_writelane_b32 v252, s36, 21
	v_writelane_b32 v252, s37, 22
	v_writelane_b32 v252, s38, 23
	v_writelane_b32 v252, s39, 24
	v_writelane_b32 v252, s40, 25
	v_writelane_b32 v252, s41, 26
	v_writelane_b32 v252, s42, 27
	v_writelane_b32 v252, s43, 28
	v_writelane_b32 v252, s44, 29
	v_writelane_b32 v252, s45, 30
	v_writelane_b32 v252, s46, 31
	v_writelane_b32 v252, s47, 32
	v_writelane_b32 v252, s48, 33
	v_writelane_b32 v252, s49, 34
	v_writelane_b32 v252, s50, 35
	v_writelane_b32 v252, s51, 36
	v_writelane_b32 v252, s52, 37
	v_writelane_b32 v252, s53, 38
	v_writelane_b32 v252, s54, 39
	v_writelane_b32 v252, s55, 40
	v_writelane_b32 v252, s56, 41
	v_writelane_b32 v252, s57, 42
	v_writelane_b32 v252, s58, 43
	v_writelane_b32 v252, s59, 44
	v_mov_b32_e32 v60, v4
	v_mov_b32_e32 v61, v5
	v_mov_b32_e32 v62, v6
	v_mov_b32_e32 v63, v7
	v_mov_b32_e32 v64, v8
	v_mov_b32_e32 v65, v9
	v_mov_b32_e32 v66, v10
	v_mov_b32_e32 v67, v11
	v_mov_b32_e32 v68, v12
	v_mov_b32_e32 v69, v13
	v_mov_b32_e32 v70, v14
	v_mov_b32_e32 v71, v15
	v_mov_b32_e32 v72, v16
	v_mov_b32_e32 v73, v18
	s_mov_b32 s99, 1
	s_branch .Lxb_entry
.Lp0_ret:
	s_mov_b32 s99, 0
	v_mov_b32_e32 v4, v60
	v_mov_b32_e32 v5, v61
	v_mov_b32_e32 v6, v62
	v_mov_b32_e32 v7, v63
	v_mov_b32_e32 v8, v64
	v_mov_b32_e32 v9, v65
	v_mov_b32_e32 v10, v66
	v_mov_b32_e32 v11, v67
	v_mov_b32_e32 v12, v68
	v_mov_b32_e32 v13, v69
	v_mov_b32_e32 v14, v70
	v_mov_b32_e32 v15, v71
	v_mov_b32_e32 v16, v72
	v_mov_b32_e32 v18, v73
	v_readlane_b32 s0, v252, 0
	v_readlane_b32 s1, v252, 1
	v_readlane_b32 s3, v252, 2
	v_readlane_b32 s4, v252, 3
	v_readlane_b32 s5, v252, 4
	v_readlane_b32 s6, v252, 5
	v_readlane_b32 s7, v252, 6
	v_readlane_b32 s8, v252, 7
	v_readlane_b32 s9, v252, 8
	v_readlane_b32 s10, v252, 9
	v_readlane_b32 s11, v252, 10
	v_readlane_b32 s12, v252, 11
	v_readlane_b32 s13, v252, 12
	v_readlane_b32 s14, v252, 13
	v_readlane_b32 s15, v252, 14
	v_readlane_b32 s16, v252, 15
	v_readlane_b32 s17, v252, 16
	v_readlane_b32 s20, v252, 17
	v_readlane_b32 s21, v252, 18
	v_readlane_b32 s22, v252, 19
	v_readlane_b32 s23, v252, 20
	v_readlane_b32 s36, v252, 21
	v_readlane_b32 s37, v252, 22
	v_readlane_b32 s38, v252, 23
	v_readlane_b32 s39, v252, 24
	v_readlane_b32 s40, v252, 25
	v_readlane_b32 s41, v252, 26
	v_readlane_b32 s42, v252, 27
	v_readlane_b32 s43, v252, 28
	v_readlane_b32 s44, v252, 29
	v_readlane_b32 s45, v252, 30
	v_readlane_b32 s46, v252, 31
	v_readlane_b32 s47, v252, 32
	v_readlane_b32 s48, v252, 33
	v_readlane_b32 s49, v252, 34
	v_readlane_b32 s50, v252, 35
	v_readlane_b32 s51, v252, 36
	v_readlane_b32 s52, v252, 37
	v_readlane_b32 s53, v252, 38
	v_readlane_b32 s54, v252, 39
	v_readlane_b32 s55, v252, 40
	v_readlane_b32 s56, v252, 41
	v_readlane_b32 s57, v252, 42
	v_readlane_b32 s58, v252, 43
	v_readlane_b32 s59, v252, 44
	s_mov_b64 s[4:5], 0
	s_barrier
	s_add_u32 s41, s30, s4
	s_addc_u32 s42, s31, s5
	s_add_u32 s6, s41, 0x2c0000
	s_addc_u32 s7, s42, 0
	s_cmpk_gt_i32 s2, 0x71
	v_mbcnt_lo_u32_b32 v22, -1, 0
	v_mbcnt_hi_u32_b32 v22, -1, v22
	v_lshl_add_u32 v22, s33, 6, v22
	s_cbranch_scc1 .LBB0_102
	s_add_u32 s10, s41, 0x323000
	s_addc_u32 s11, s42, 0
	s_cmp_lt_i32 s2, 8
	s_cbranch_scc1 .LBB0_76
	s_cmp_gt_u32 s2, 13
	s_cbranch_scc0 .LBB0_77
	s_cmp_gt_u32 s2, 17
	s_cbranch_scc0 .LBB0_78
	s_cmp_gt_u32 s2, 25
	s_cbranch_scc0 .LBB0_79
	s_add_i32 s8, s2, 0xffe6
	s_bfe_u32 s9, s8, 0x70001
	s_mulk_i32 s9, 0xbb
	s_bfe_u32 s9, s9, 0x5000b
	v_readlane_b32 s44, v253, 17
	s_mul_i32 s10, s9, 0x1600000
	v_readlane_b32 s58, v253, 31
	v_readlane_b32 s59, v253, 32
	s_add_u32 s58, s18, s10
	v_readlane_b32 s45, v253, 18
	v_readlane_b32 s46, v253, 19
	v_readlane_b32 s47, v253, 20
	v_readlane_b32 s48, v253, 21
	v_readlane_b32 s49, v253, 22
	v_readlane_b32 s50, v253, 23
	v_readlane_b32 s51, v253, 24
	v_readlane_b32 s52, v253, 25
	v_readlane_b32 s53, v253, 26
	v_readlane_b32 s54, v253, 27
	v_readlane_b32 s55, v253, 28
	v_readlane_b32 s56, v253, 29
	v_readlane_b32 s57, v253, 30
	s_addc_u32 s59, s19, 0
	v_writelane_b32 v253, s44, 17
	s_mul_i32 s10, s9, 0x12000
	s_add_u32 s10, s6, s10
	v_writelane_b32 v253, s45, 18
	v_writelane_b32 v253, s46, 19
	v_writelane_b32 v253, s47, 20
	v_writelane_b32 v253, s48, 21
	v_writelane_b32 v253, s49, 22
	v_writelane_b32 v253, s50, 23
	v_writelane_b32 v253, s51, 24
	v_writelane_b32 v253, s52, 25
	s_addc_u32 s11, s7, 0
	v_writelane_b32 v253, s53, 26
	s_add_u32 s12, s10, 0x3000
	v_writelane_b32 v253, s54, 27
	s_addc_u32 s13, s11, 0
	s_mul_i32 s10, s9, 0x10800
	v_writelane_b32 v253, s55, 28
	s_add_u32 s10, s41, s10
	v_writelane_b32 v253, s56, 29
	s_addc_u32 s11, s42, 0
	v_writelane_b32 v253, s57, 30
	s_add_u32 s10, s10, 0x33b000
	s_mul_i32 s9, s9, 22
	v_writelane_b32 v253, s58, 31
	s_addc_u32 s11, s11, 0
	s_sub_i32 s8, s8, s9
	v_writelane_b32 v253, s59, 32
	s_and_b32 s36, s8, 0xff
	s_mov_b64 s[14:15], 0
	s_branch .LBB0_80

; __device__ __forceinline__ int otid(int wv) { int t; asm volatile("v_mbcnt_lo_u32_b32 %0, -1, 0\n\tv_mbcnt_hi_u32_b32 %0, -1, %0\n\tv_lshl_add_u32 %0, %1, 6, %0" : "=&v"(t) : "s"(wv)); return t; }
; __device__ __forceinline__ unsigned xb_ld(unsigned* p)              { return __hip_atomic_load(p, __ATOMIC_RELAXED, __HIP_MEMORY_SCOPE_AGENT); }
; __device__ __forceinline__ unsigned xb_xcc_id() { return (unsigned)__builtin_amdgcn_s_getreg((3 << 11) | 20) & 0xFu; }
; __device__ __forceinline__ void xcd_barrier_complete(unsigned* bar, unsigned x, unsigned& nloc, unsigned& nx) {
;     const unsigned G = gridDim.x * gridDim.y * gridDim.z;
;     unsigned sum, cnt, mine, sp = 0u;
;     for (;;) {
;         sum = 0u; cnt = 0u; mine = 0u;
; #pragma unroll
;         for (unsigned j = 0; j < 16; ++j) { const unsigned c = xb_ld(&bar[XB_XCNT(j)]); sum += c; cnt += (c > 0u) ? 1u : 0u; mine = (j == x) ? c : mine; }
;         if (sum == G) break;
; __device__ __forceinline__ void xcd_barrier(const XcdBarrier& b, int wv) {
;     asm volatile("s_waitcnt vmcnt(0)" ::: "memory");
;     __syncthreads();
;     if (otid(wv) == 0) {
;         unsigned* bar = b.bar;
;         unsigned bx = (unsigned)__builtin_amdgcn_readfirstlane((int)xb_xcc_id()); asm volatile("" : "+s"(bx));
;         __builtin_amdgcn_s_waitcnt(0);
;         unsigned nloc = b.st[0], nx = b.st[1];
;         if (nloc == 0u) { xcd_barrier_complete(bar, bx, nloc, nx); b.st[0] = nloc; b.st[1] = nx; }
.Lxb_entry:
	s_waitcnt vmcnt(0)
	s_barrier
	v_mbcnt_lo_u32_b32 v0, -1, 0
	v_mbcnt_hi_u32_b32 v0, -1, v0
	v_lshl_add_u32 v0, s33, 6, v0
	s_nop 0
	v_cmp_eq_u32_e32 vcc, 0, v0
	s_and_saveexec_b64 s[0:1], vcc
	s_cbranch_execz .LBB0_176
	s_getreg_b32 s3, hwreg(HW_REG_XCC_ID, 0, 4)
	s_add_i32 s4, 0, 0x23ff0
	s_and_b32 s3, s3, 15
	v_mov_b32_e32 v0, s4
	s_waitcnt vmcnt(0) expcnt(0) lgkmcnt(0)
	ds_read_b32 v2, v0
	s_add_i32 s4, 0, 0x23ff4
	v_mov_b32_e32 v0, s4
	ds_read_b32 v0, v0
	s_waitcnt lgkmcnt(1)
	v_cmp_ne_u32_e32 vcc, 0, v2
	s_cbranch_vccnz .LBB0_140
	s_add_u32 s4, s30, 0x3e9200
	s_addc_u32 s5, s31, 0
	s_add_u32 s6, s30, 0x3e9400
	s_addc_u32 s7, s31, 0
	s_add_u32 s8, s30, 0x3e9500
	s_addc_u32 s9, s31, 0
	s_add_u32 s10, s30, 0x3e9600
	s_addc_u32 s11, s31, 0
	s_add_u32 s12, s30, 0x3e9700
	s_addc_u32 s13, s31, 0
	s_add_u32 s14, s30, 0x3e9800
	s_addc_u32 s15, s31, 0
	s_add_u32 s16, s30, 0x3e9900
	s_addc_u32 s17, s31, 0
	s_add_u32 s20, s30, 0x3e9a00
	s_addc_u32 s21, s31, 0
	s_add_u32 s22, s30, 0x3e9b00
	s_addc_u32 s23, s31, 0
	s_add_u32 s36, s30, 0x3e9c00
	s_addc_u32 s37, s31, 0
	s_add_u32 s38, s30, 0x3e9d00
	s_addc_u32 s39, s31, 0
	s_add_u32 s40, s30, 0x3e9e00
	s_addc_u32 s41, s31, 0
	s_add_u32 s42, s30, 0x3e9f00
	s_addc_u32 s43, s31, 0
	s_add_u32 s44, s30, 0x3ea000
	s_addc_u32 s45, s31, 0
	s_add_u32 s46, s30, 0x3ea100
	s_addc_u32 s47, s31, 0
	s_add_u32 s48, s30, 0x3ea200
	s_addc_u32 s49, s31, 0
	s_mul_i32 s58, s35, s62
	s_add_u32 s50, s30, 0x3ea300
	s_mul_i32 s58, s58, s34
	s_addc_u32 s51, s31, 0
	s_mov_b32 s59, 1
	v_mov_b32_e32 v16, 0
	s_branch .LBB0_128

; #define LAS __attribute__((address_space(3)))
; __device__ __forceinline__ void xcd_barrier(const XcdBarrier& b, int wv) {
;     ...
;     }
;     __syncthreads();
; }
; __global__ void __launch_bounds__(NTHR, 2) mega(Params p) {
;     ...
;     LAS unsigned char* ldsl = (LAS unsigned char*)lds;
;     for (int i = 0; i < 4; ++i) {
;         WSPTRS
;         const int kind = i % 3, jl = i / 3;
;         {   pg8::StaticOrder S; const u64* ssin = ssb + (size_t)(2 * i) * MTOK;
;             if (kind == 0) { pg8::Gemm g{xb, wain + (size_t)jl * 2048 * 1024, MTOK, 2048, 1024, 1024}; S.init(MTOK, 2048, G, bid);
;                 pg8::EpiAct<1> E{big1, 2048, biasG1 + (size_t)i * 3 * 2048, 2048, ssin, ssb + (size_t)(9 + jl) * MTOK, 1024};
.LBB0_176:
	s_or_b64 exec, exec, s[0:1]
	s_cmp_eq_u32 s99, 1
	s_cbranch_scc1 .Lp0_ret
	s_ashr_i32 s3, s2, 31
	s_lshr_b32 s1, s3, 29
	s_add_i32 s1, s2, s1
	s_ashr_i32 s10, s1, 3
	s_and_b32 s1, s1, -8
	s_mul_i32 s0, s35, s34
	s_sub_i32 s8, s2, s1
	s_ashr_i32 s35, s34, 31
	s_cmpk_lt_i32 s2, 0x400
	s_cselect_b64 s[4:5], -1, 0
	v_writelane_b32 v253, s4, 35
	s_mul_i32 s71, s0, s62
	s_waitcnt lgkmcnt(0)
	v_mov_b32_e32 v0, 0
	v_writelane_b32 v253, s5, 36
	s_lshl_b32 s4, s8, 7
	s_add_u32 s78, s30, 0x3e9200
	s_addc_u32 s79, s31, 0
	s_add_u32 s72, s30, 0x3e9400
	s_addc_u32 s73, s31, 0
	s_add_u32 s6, s30, 0x3e9500
	s_addc_u32 s7, s31, 0
	v_writelane_b32 v253, s6, 37
	v_mov_b32_e32 v251, 0x358637bd
	v_mbcnt_hi_u32_b32 v250, -1, v17
	v_writelane_b32 v253, s7, 38
	s_add_u32 s6, s30, 0x3e9600
	s_addc_u32 s7, s31, 0
	v_writelane_b32 v253, s6, 39
	v_mov_b32_e32 v178, 0x3e000000
	v_mov_b32_e32 v252, 0xf149f2ca
	v_writelane_b32 v253, s7, 40
	s_add_u32 s6, s30, 0x3e9700
	s_addc_u32 s7, s31, 0
	v_writelane_b32 v253, s6, 41
	s_movk_i32 s43, 0x81
	s_movk_i32 s45, 0x1600
	v_writelane_b32 v253, s7, 42
	s_add_u32 s6, s30, 0x3e9800
	s_addc_u32 s7, s31, 0
	v_writelane_b32 v253, s6, 43
	s_mov_b32 s37, 0
	s_mov_b64 s[38:39], 0x80
	v_writelane_b32 v253, s7, 44
	s_add_u32 s6, s30, 0x3e9900
	s_addc_u32 s7, s31, 0
	v_writelane_b32 v253, s6, 45
	s_barrier
	s_nop 0
	v_writelane_b32 v253, s7, 46
	s_add_u32 s6, s30, 0x3e9a00
	s_addc_u32 s7, s31, 0
	v_writelane_b32 v253, s6, 47
	s_nop 1
	v_writelane_b32 v253, s7, 48
	s_add_u32 s6, s30, 0x3e9b00
	s_addc_u32 s7, s31, 0
	v_writelane_b32 v253, s6, 49
	s_nop 1
	v_writelane_b32 v253, s7, 50
	s_add_u32 s6, s30, 0x3e9c00
	s_addc_u32 s7, s31, 0
	v_writelane_b32 v253, s6, 51
	s_nop 1
	v_writelane_b32 v253, s7, 52
	s_add_u32 s6, s30, 0x3e9d00
	s_addc_u32 s7, s31, 0
	v_writelane_b32 v253, s6, 53
	s_nop 1
	v_writelane_b32 v253, s7, 54
	s_add_u32 s6, s30, 0x3e9e00
	s_addc_u32 s7, s31, 0
	v_writelane_b32 v253, s6, 55
	s_nop 1
	v_writelane_b32 v253, s7, 56
	s_add_u32 s6, s30, 0x3e9f00
	s_addc_u32 s7, s31, 0
	v_writelane_b32 v253, s6, 57
	s_nop 1
	v_writelane_b32 v253, s7, 58
	s_add_u32 s6, s30, 0x3ea000
	s_addc_u32 s7, s31, 0
	v_writelane_b32 v253, s6, 59
	s_nop 1
	v_writelane_b32 v253, s7, 60
	s_add_u32 s6, s30, 0x3ea100
	s_addc_u32 s7, s31, 0
	v_writelane_b32 v253, s6, 61
	s_nop 1
	v_writelane_b32 v253, s7, 62
	s_add_u32 s6, s30, 0x3ea200
	s_addc_u32 s7, s31, 0
	v_writelane_b32 v253, s6, 63
	s_nop 0
	v_readlane_b32 s1, v253, 33
	v_writelane_b32 v254, s7, 0
	s_add_u32 s6, s30, 0x3ea300
	s_addc_u32 s7, s31, 0
	v_writelane_b32 v254, s6, 1
	s_nop 1
	v_writelane_b32 v254, s7, 2
	s_add_u32 s6, s30, 0x3ec400
	s_addc_u32 s7, s31, 0
	s_add_u32 s80, s30, 0x3ec500
	s_addc_u32 s81, s31, 0
	v_writelane_b32 v254, s6, 3
	s_cmpk_lt_i32 s1, 0x160
	v_readlane_b32 s1, v253, 34
	v_writelane_b32 v254, s7, 4
	s_cselect_b64 s[6:7], -1, 0
	v_writelane_b32 v254, s6, 5
	s_cmpk_lt_i32 s1, 0xb0
	v_writelane_b32 v255, s80, 0
	v_writelane_b32 v254, s7, 6
	s_cselect_b64 s[6:7], -1, 0
	s_add_u32 s76, s30, 0x83ec600
	s_addc_u32 s77, s31, 0
	v_writelane_b32 v254, s6, 7
	s_cmpk_lt_i32 s2, 0x800
	v_writelane_b32 v255, s81, 1
	v_writelane_b32 v254, s7, 8
	s_cselect_b64 s[6:7], -1, 0
	s_lshr_b32 s1, s34, 31
	s_add_i32 s1, s34, s1
	s_ashr_i32 s93, s1, 1
	v_writelane_b32 v254, s6, 9
	s_cmp_ge_i32 s2, s93
	v_writelane_b32 v255, s72, 2
	v_writelane_b32 v254, s7, 10
	s_cselect_b64 s[6:7], -1, 0
	v_writelane_b32 v254, s6, 11
	s_sub_i32 s1, s2, s93
	s_sub_i32 s40, s34, s93
	v_writelane_b32 v254, s7, 12
	s_add_u32 s6, s30, 0x103ec600
	s_addc_u32 s7, s31, 0
	s_add_u32 s96, s30, 0x3d9000
	s_addc_u32 s97, s31, 0
	s_add_u32 s84, s30, 0x3e1000
	s_addc_u32 s85, s31, 0
	v_writelane_b32 v254, s6, 13
	s_cmpk_lt_i32 s1, 0x400
	v_writelane_b32 v255, s73, 3
	v_writelane_b32 v254, s7, 14
	s_cselect_b64 s[6:7], -1, 0
	s_add_u32 s86, s30, 0x3d5000
	s_addc_u32 s87, s31, 0
	s_add_u32 s88, s30, 0x3d7000
	v_writelane_b32 v254, s1, 15
	s_addc_u32 s89, s31, 0
	v_writelane_b32 v254, s6, 16
	s_cmpk_lt_i32 s2, 0xb00
	v_writelane_b32 v255, s71, 4
	v_writelane_b32 v254, s7, 17
	s_cselect_b64 s[6:7], -1, 0
	v_writelane_b32 v254, s6, 18
	s_add_u32 s0, s30, 0x133ec600
	s_addc_u32 s1, s31, 0
;     __device__ bool next(int i, Unit& u) const {
;         const long L = (long)i * G + c; if (L >= nwg) return false;
;         int wgid = (int)L; { const int q = nwg / NXCD, r = nwg % NXCD, xcd = wgid % NXCD, off = wgid / NXCD; wgid = (xcd < r ? xcd * (q + 1) : r * (q + 1) + (xcd - r) * q) + off; }
;         const int nig = WGM * nN, gid = wgid / nig, fm = gid * WGM, gsz = (nM - fm) < WGM ? (nM - fm) : WGM;
;         u.pm = fm + ((wgid % nig) % gsz); u.pn = (wgid % nig) / gsz; return true;
;     }
; __global__ void __launch_bounds__(NTHR, 2) mega(Params p) {
;     ...
;     for (int i = 0; i < 4; ++i) {
;         WSPTRS
;         const int kind = i % 3, jl = i / 3;
;         {   pg8::StaticOrder S; const u64* ssin = ssb + (size_t)(2 * i) * MTOK;
;             if (kind == 0) { pg8::Gemm g{xb, wain + (size_t)jl * 2048 * 1024, MTOK, 2048, 1024, 1024}; S.init(MTOK, 2048, G, bid);
;                 pg8::EpiAct<1> E{big1, 2048, biasG1 + (size_t)i * 3 * 2048, 2048, ssin, ssb + (size_t)(9 + jl) * MTOK, 1024};
	v_writelane_b32 v254, s7, 19
	v_writelane_b32 v254, s0, 20
	v_writelane_b32 v255, s84, 5
	s_nop 0
	v_writelane_b32 v254, s1, 21
	s_add_u32 s0, s30, 0x37d000
	v_writelane_b32 v254, s0, 22
	s_addc_u32 s0, s31, 0
	s_lshl_b32 s41, s34, 9
	s_cmpk_lt_i32 s2, 0x200
	v_writelane_b32 v254, s0, 23
	s_cselect_b64 s[0:1], -1, 0
	s_lshl_b32 s5, s8, 6
	v_writelane_b32 v254, s0, 24
	s_cmp_lt_i32 s8, 0
	v_writelane_b32 v255, s85, 6
	v_writelane_b32 v254, s1, 25
	s_cselect_b64 s[0:1], -1, 0
	v_writelane_b32 v254, s0, 26
	v_writelane_b32 v255, s86, 7
	s_nop 0
	v_writelane_b32 v254, s1, 27
	s_and_b64 s[0:1], s[0:1], exec
	s_mul_i32 s0, s8, 0x81
	s_cselect_b32 s0, s0, s4
	s_mul_i32 s1, s8, 0x41
	s_movk_i32 s4, 0x161
	s_cselect_b32 s1, s1, s5
	s_cselect_b32 s4, s4, 0x160
	s_add_i32 s0, s0, s10
	s_ashr_i32 s5, s0, 31
	s_lshr_b32 s5, s5, 26
	s_add_i32 s5, s0, s5
	s_and_b32 s6, s5, 0xffc0
	s_sub_i32 s0, s0, s6
	s_bfe_i32 s6, s0, 0x80000
	s_bfe_u32 s6, s6, 0x3000c
	s_add_i32 s6, s0, s6
	s_mul_i32 s4, s8, s4
	s_and_b32 s7, s6, 0xf8
	s_add_i32 s4, s4, s10
	s_sub_i32 s0, s0, s7
	s_mul_hi_i32 s7, s4, 0x2e8ba2e9
	v_writelane_b32 v254, s8, 28
	s_lshr_b32 s8, s7, 31
	s_ashr_i32 s7, s7, 5
	s_add_i32 s7, s7, s8
	s_mul_i32 s8, s7, 0xb0
	s_sub_i32 s4, s4, s8
	s_bfe_u32 s8, s4, 0x3001c
	s_add_i32 s8, s4, s8
	s_and_b32 s9, s8, 0xfff8
	s_add_i32 s1, s1, s10
	s_sub_i32 s4, s4, s9
	s_ashr_i32 s9, s1, 31
	s_lshr_b32 s9, s9, 27
	s_add_i32 s9, s1, s9
	v_writelane_b32 v254, s10, 29
	s_and_b32 s10, s9, 0xffe0
	s_sub_i32 s1, s1, s10
	s_bfe_i32 s10, s1, 0x80000
	s_bfe_u32 s10, s10, 0x3000c
	s_add_i32 s10, s1, s10
	s_and_b32 s11, s10, 0xf8
	s_sub_i32 s1, s1, s11
	s_ashr_i32 s9, s9, 5
	s_lshl_b32 s9, s9, 3
	s_sext_i32_i8 s1, s1
	s_add_i32 s1, s9, s1
	v_writelane_b32 v254, s1, 30
	s_ashr_i32 s1, s5, 6
	s_lshl_b32 s1, s1, 3
	s_sext_i32_i8 s0, s0
	s_bfe_i32 s5, s6, 0x80000
	s_add_i32 s12, s1, s0
	s_lshl_b32 s0, s7, 3
	s_sext_i32_i16 s1, s4
	s_sext_i32_i16 s5, s5
	s_sext_i32_i16 s6, s8
	s_add_i32 s8, s0, s1
	s_bfe_i32 s0, s10, 0x80000
	s_sext_i32_i16 s4, s0
	s_ashr_i32 s0, s5, 3
	v_writelane_b32 v254, s0, 31
	s_lshr_b32 s0, s5, 3
	s_bfe_i64 s[0:1], s[0:1], 0x100000
	s_lshl_b64 s[0:1], s[0:1], 19
	v_writelane_b32 v254, s0, 32
	s_ashr_i32 s13, s12, 31
	s_ashr_i32 s9, s8, 31
	v_writelane_b32 v254, s1, 33
	s_ashr_i32 s0, s6, 3
	v_writelane_b32 v254, s0, 34
	s_lshr_b32 s0, s6, 3
	s_bfe_i64 s[0:1], s[0:1], 0x100000
	s_lshl_b64 s[0:1], s[0:1], 19
	v_writelane_b32 v254, s0, 35
	s_lshl_b32 s92, s34, 7
	v_writelane_b32 v255, s87, 8
	v_writelane_b32 v254, s1, 36
	s_ashr_i32 s0, s4, 3
	v_writelane_b32 v254, s0, 37
	s_lshr_b32 s0, s4, 3
	s_bfe_i64 s[0:1], s[0:1], 0x100000
	v_writelane_b32 v254, s0, 38
	v_writelane_b32 v255, s88, 9
	s_mov_b32 s4, 0
	v_writelane_b32 v254, s1, 39
	s_lshl_b32 s0, s2, 7
	v_writelane_b32 v254, s0, 40
	s_lshl_b32 s0, s2, 4
	v_writelane_b32 v254, s0, 41
	s_lshl_b32 s0, s34, 4
	v_writelane_b32 v254, s0, 42
	s_mov_b32 s0, s12
	v_writelane_b32 v254, s0, 43
	v_writelane_b32 v255, s89, 10
	v_writelane_b32 v255, s92, 11
	v_writelane_b32 v254, s1, 44
	s_lshl_b64 s[0:1], s[12:13], 19
	v_writelane_b32 v254, s0, 45
	v_writelane_b32 v255, s82, 12
	s_nop 0
	v_writelane_b32 v254, s1, 46
	s_mov_b32 s0, s8
	v_writelane_b32 v254, s0, 47
	v_writelane_b32 v255, s83, 13
	v_writelane_b32 v255, s93, 14
	v_writelane_b32 v254, s1, 48
	s_lshl_b64 s[0:1], s[8:9], 19
	v_writelane_b32 v254, s0, 49
	v_writelane_b32 v255, s40, 15
	v_writelane_b32 v255, s96, 16
	v_writelane_b32 v254, s1, 50
	s_add_u32 s0, s30, 0x83ec640
	s_addc_u32 s1, s31, 0
	v_writelane_b32 v254, s0, 51
	v_writelane_b32 v255, s97, 17
	v_writelane_b32 v255, s41, 18
	v_writelane_b32 v254, s1, 52
	s_lshl_b32 s0, s2, 11
	v_writelane_b32 v254, s0, 53
	s_lshl_b32 s0, s2, 12
	v_writelane_b32 v254, s0, 54
	s_add_i32 s0, 0, 0x23ff0
	v_writelane_b32 v254, s0, 55
	s_add_i32 s0, 0, 0x23ff4
	v_writelane_b32 v254, s0, 56
	s_add_i32 s0, 0, 0x11000
	v_writelane_b32 v254, s0, 57
	s_add_i32 s0, 0, 0x4800
	v_writelane_b32 v254, s0, 58
	s_add_i32 s0, 0, 0x19800
	v_writelane_b32 v254, s0, 59
	v_writelane_b32 v254, s76, 60
	s_nop 1
	v_writelane_b32 v254, s77, 61
	v_writelane_b32 v254, s78, 62
	s_nop 1
	v_writelane_b32 v254, s79, 63
	s_branch .LBB0_178
